# conv epilogue fast copy also drops the per-row token-range test (taken only when the tile's 254 rows are all inside the stream)
# speedup vs baseline: 1.0112x; 1.0010x over previous
; template <int EPI>
; DI void phase_gemm(const Params& p, const GemmArgs& ga, char* lds) {
;     ...
;         const int R0 = 1 + seg * 16;
;         const int Rend = (R0 + 16 < 255) ? (R0 + 16) : 255;
;         auto ld4 = [&](const char* b_, int R) -> float4 {
;           const u32x2 u = *(const u32x2*)(b_ + R * RS);
;           float4 f = {__uint_as_float(u.x << 16), __uint_as_float(u.x & 0xffff0000u), __uint_as_float(u.y << 16), __uint_as_float(u.y & 0xffff0000u)};
;           return f;
;         };
;         float4 pg = ld4(gbase, R0 - 1), pvv = ld4(vbase, R0 - 1);
;         float4 cg_ = ld4(gbase, R0), cv_ = ld4(vbase, R0);
;         u16* Aout = (u16*)(p.ws + OFF_BIG) + (ptrdiff_t)(tokbase + pos0) * DFF + ch;
; #pragma unroll 4
;         for (int R = R0; R < Rend; ++R) {
;           const float4 ng = ld4(gbase, R + 1), nv = ld4(vbase, R + 1);
;           if (pos0 + R < S) {
;             const int tflat = pos0 + R;
;             const int ps = (tflat < NTOK_P) ? (tflat & (SP - 1)) : ((tflat - NTOK_P) & (SS - 1));
;             const int Ss = (tflat < NTOK_P) ? SP : SS;
.LBB0_68:
	s_or_b64 exec, exec, s[14:15]
	s_and_b64 exec, exec, s[8:9]
	s_cbranch_execz .LBB0_54
	s_mul_i32 s10, s20, 0x1600
	s_mul_hi_i32 s11, s20, 0x1600
	s_add_u32 s10, s2, s10
	s_addc_u32 s11, s3, s11
	s_add_i32 s14, s27, -2
	v_lshl_add_u64 v[38:39], s[10:11], 0, v[46:47]
	s_mul_hi_i32 s10, s14, 0x1600
	s_mul_i32 s11, s14, 0x1600
	v_add_u32_e32 v48, 1, v0
	v_mov_b32_e32 v42, s11
	v_mov_b32_e32 v43, s10
	v_mad_i64_i32 v[48:49], s[10:11], v48, s36, 0
	v_mad_i64_i32 v[42:43], s[10:11], v0, s36, v[42:43]
	v_readlane_b32 s16, v254, 43
	v_mad_i64_i32 v[48:49], s[10:11], s14, v216, v[48:49]
	v_lshl_add_u64 v[42:43], v[42:43], 0, v[46:47]
	v_readlane_b32 s17, v254, 44
	v_lshl_add_u64 v[46:47], v[48:49], 0, v[46:47]
	v_mad_u64_u32 v[48:49], s[10:11], v0, s35, v[156:157]
	v_lshl_add_u64 v[42:43], s[16:17], 0, v[42:43]
	v_lshl_add_u64 v[46:47], s[16:17], 0, v[46:47]
	s_mov_b64 s[14:15], 0
	s_waitcnt vmcnt(0)
	s_ashr_i32 s10, s20, 11
	s_add_i32 s11, s20, 0xff
	s_ashr_i32 s11, s11, 11
	s_cmp_eq_u32 s10, s11
	s_cbranch_scc0 .LBB0_71
	s_cmp_lt_i32 s20, 0xbf02
	s_cbranch_scc1 .Lcf0_h
	s_branch .LBB0_71

; DI float fexp2(float x) { return __builtin_amdgcn_exp2f(x); }
; template <int EPI>
; DI void phase_gemm(const Params& p, const GemmArgs& ga, char* lds) {
;     ...
; #pragma unroll 4
;         for (int R = R0; R < Rend; ++R) {
;           const float4 ng = ld4(gbase, R + 1), nv = ld4(vbase, R + 1);
;           if (pos0 + R < S) {
;             const int tflat = pos0 + R;
;             const int ps = (tflat < NTOK_P) ? (tflat & (SP - 1)) : ((tflat - NTOK_P) & (SS - 1));
;             const int Ss = (tflat < NTOK_P) ? SP : SS;
;             const float mp = (ps == 0) ? 0.f : 1.f;
;             const float mn = (ps == Ss - 1) ? 0.f : 1.f;
;             float g[4], v[4];
;             g[0] = mp * pg.x * wg[0].x + cg_.x * wg[1].x + mn * ng.x * wg[2].x + bg.x;
;             g[1] = mp * pg.y * wg[0].y + cg_.y * wg[1].y + mn * ng.y * wg[2].y + bg.y;
;             g[2] = mp * pg.z * wg[0].z + cg_.z * wg[1].z + mn * ng.z * wg[2].z + bg.z;
;             g[3] = mp * pg.w * wg[0].w + cg_.w * wg[1].w + mn * ng.w * wg[2].w + bg.w;
;             v[0] = mp * pvv.x * wv[0].x + cv_.x * wv[1].x + mn * nv.x * wv[2].x + bv.x;
;             v[1] = mp * pvv.y * wv[0].y + cv_.y * wv[1].y + mn * nv.y * wv[2].y + bv.y;
;             v[2] = mp * pvv.z * wv[0].z + cv_.z * wv[1].z + mn * nv.z * wv[2].z + bv.z;
;             v[3] = mp * pvv.w * wv[0].w + cv_.w * wv[1].w + mn * nv.w * wv[2].w + bv.w;
;             float a_[4];
; #pragma unroll
;             for (int e = 0; e < 4; ++e) a_[e] = g[e] * __builtin_amdgcn_rcpf(1.f + fexp2(-1.4426950408889634f * g[e])) * v[e];
;             u32x2 ov = {pk_bf16(a_[0], a_[1]), pk_bf16(a_[2], a_[3])};
;             *(u32x2*)(Aout + (ptrdiff_t)R * DFF) = ov;
;           }
;           pg = cg_; pvv = cv_; cg_ = ng; cv_ = nv;
;         }
.Lcf0_l:
	v_add_u32_e32 v0, 4, v0
	v_cmp_ge_i32_e64 s[10:11], v0, v170
	v_lshl_add_u64 v[42:43], v[42:43], 0, s[86:87]
	v_lshl_add_u64 v[46:47], v[46:47], 0, s[86:87]
	s_or_b64 s[14:15], s[10:11], s[14:15]
	v_add_u32_e32 v48, 0x820, v48
	s_andn2_b64 exec, exec, s[14:15]
	s_cbranch_execz .LBB0_54
.Lcf0_h:
	ds_read2_b64 v[60:63], v48 offset1:32
	v_add_u32_e32 v49, s27, v0
	v_add_u32_e32 v58, -1, v49
	s_waitcnt lgkmcnt(0)
	v_lshlrev_b32_e32 v68, 16, v60
	v_and_b32_e32 v69, 0xffff0000, v60
	v_lshlrev_b32_e32 v60, 16, v61
	v_and_b32_e32 v61, 0xffff0000, v61
	v_lshlrev_b32_e32 v72, 16, v62
	v_and_b32_e32 v73, 0xffff0000, v62
	v_lshlrev_b32_e32 v64, 16, v63
	v_and_b32_e32 v65, 0xffff0000, v63
	v_pk_mul_f32 v[66:67], v[10:11], v[40:41]
	v_pk_mul_f32 v[70:71], v[12:13], v[34:35]
	v_pk_fma_f32 v[56:57], v[2:3], v[56:57], v[66:67]
	v_pk_fma_f32 v[56:57], v[18:19], v[68:69], v[56:57]
	v_pk_mul_f32 v[54:55], v[6:7], v[54:55]
	v_pk_add_f32 v[56:57], v[26:27], v[56:57]
	v_pk_fma_f32 v[54:55], v[14:15], v[44:45], v[54:55]
	v_mul_f32_e32 v59, 0xbfb8aa3b, v56
	v_exp_f32_e32 v59, v59
	v_pk_fma_f32 v[54:55], v[22:23], v[72:73], v[54:55]
	v_add_f32_e32 v59, 1.0, v59
	v_rcp_f32_e32 v66, v59
	v_mul_f32_e32 v59, 0xbfb8aa3b, v57
	v_exp_f32_e32 v59, v59
	v_pk_add_f32 v[54:55], v[30:31], v[54:55]
	v_add_f32_e32 v59, 1.0, v59
	v_rcp_f32_e32 v67, v59
	v_pk_fma_f32 v[52:53], v[4:5], v[52:53], v[70:71]
	v_pk_mul_f32 v[56:57], v[56:57], v[66:67]
	v_pk_mul_f32 v[50:51], v[8:9], v[50:51]
	v_pk_mul_f32 v[54:55], v[54:55], v[56:57]
	v_pk_fma_f32 v[52:53], v[20:21], v[60:61], v[52:53]
	v_pk_fma_f32 v[50:51], v[16:17], v[36:37], v[50:51]
	v_pk_add_f32 v[52:53], v[28:29], v[52:53]
	v_pk_fma_f32 v[50:51], v[24:25], v[64:65], v[50:51]
	v_mul_f32_e32 v56, 0xbfb8aa3b, v52
	v_mul_f32_e32 v57, 0xbfb8aa3b, v53
	v_exp_f32_e32 v56, v56
	v_exp_f32_e32 v57, v57
	v_pk_add_f32 v[50:51], v[32:33], v[50:51]
	v_add_f32_e32 v56, 1.0, v56
	v_add_f32_e32 v57, 1.0, v57
	v_rcp_f32_e32 v56, v56
	v_rcp_f32_e32 v57, v57
	s_nop 0
	v_pk_mul_f32 v[52:53], v[52:53], v[56:57]
	s_nop 0
	v_pk_mul_f32 v[50:51], v[50:51], v[52:53]
	v_cvt_pk_bf16_f32 v52, v54, v55
	v_cvt_pk_bf16_f32 v53, v50, v51
	global_store_dwordx2 v[42:43], v[52:53], off
.Lcf0_s0:
	ds_read2_b64 v[50:53], v48 offset0:65 offset1:97
	s_waitcnt lgkmcnt(0)
	v_lshlrev_b32_e32 v66, 16, v50
	v_and_b32_e32 v67, 0xffff0000, v50
	v_lshlrev_b32_e32 v58, 16, v51
	v_and_b32_e32 v59, 0xffff0000, v51
	v_lshlrev_b32_e32 v70, 16, v52
	v_and_b32_e32 v71, 0xffff0000, v52
	v_lshlrev_b32_e32 v62, 16, v53
	v_and_b32_e32 v63, 0xffff0000, v53
	v_pk_mul_f32 v[54:55], v[10:11], v[68:69]
	v_pk_mul_f32 v[56:57], v[12:13], v[60:61]
	v_pk_fma_f32 v[40:41], v[2:3], v[40:41], v[54:55]
	v_pk_fma_f32 v[40:41], v[18:19], v[66:67], v[40:41]
	v_pk_mul_f32 v[44:45], v[6:7], v[44:45]
	v_pk_add_f32 v[40:41], v[26:27], v[40:41]
	v_pk_fma_f32 v[44:45], v[14:15], v[72:73], v[44:45]
	v_mul_f32_e32 v51, 0xbfb8aa3b, v40
	v_exp_f32_e32 v51, v51
	v_pk_fma_f32 v[44:45], v[22:23], v[70:71], v[44:45]
	v_add_f32_e32 v51, 1.0, v51
	v_rcp_f32_e32 v54, v51
	v_mul_f32_e32 v51, 0xbfb8aa3b, v41
	v_exp_f32_e32 v51, v51
	v_pk_add_f32 v[44:45], v[30:31], v[44:45]
	v_add_f32_e32 v51, 1.0, v51
	v_rcp_f32_e32 v55, v51
	v_pk_fma_f32 v[34:35], v[4:5], v[34:35], v[56:57]
	v_pk_mul_f32 v[40:41], v[40:41], v[54:55]
	v_pk_mul_f32 v[36:37], v[8:9], v[36:37]
	v_pk_mul_f32 v[40:41], v[44:45], v[40:41]
	v_pk_fma_f32 v[34:35], v[20:21], v[58:59], v[34:35]
	v_pk_fma_f32 v[36:37], v[16:17], v[64:65], v[36:37]
	v_pk_add_f32 v[34:35], v[28:29], v[34:35]
	v_pk_fma_f32 v[36:37], v[24:25], v[62:63], v[36:37]
	v_mul_f32_e32 v44, 0xbfb8aa3b, v34
	v_mul_f32_e32 v45, 0xbfb8aa3b, v35
	v_exp_f32_e32 v44, v44
	v_exp_f32_e32 v45, v45
	v_pk_add_f32 v[36:37], v[32:33], v[36:37]
	v_add_f32_e32 v44, 1.0, v44
	v_add_f32_e32 v45, 1.0, v45
	v_rcp_f32_e32 v44, v44
	v_rcp_f32_e32 v45, v45
	s_nop 0
	v_pk_mul_f32 v[34:35], v[34:35], v[44:45]
	s_nop 0
	v_pk_mul_f32 v[34:35], v[36:37], v[34:35]
	v_cvt_pk_bf16_f32 v36, v40, v41
	v_cvt_pk_bf16_f32 v37, v34, v35
	global_store_dwordx2 v[46:47], v[36:37], off
; DI float fexp2(float x) { return __builtin_amdgcn_exp2f(x); }
; template <int EPI>
; DI void phase_gemm(const Params& p, const GemmArgs& ga, char* lds) {
;     ...
; #pragma unroll 4
;         for (int R = R0; R < Rend; ++R) {
;           const float4 ng = ld4(gbase, R + 1), nv = ld4(vbase, R + 1);
;           if (pos0 + R < S) {
;             const int tflat = pos0 + R;
;             const int ps = (tflat < NTOK_P) ? (tflat & (SP - 1)) : ((tflat - NTOK_P) & (SS - 1));
;             const int Ss = (tflat < NTOK_P) ? SP : SS;
;             const float mp = (ps == 0) ? 0.f : 1.f;
;             const float mn = (ps == Ss - 1) ? 0.f : 1.f;
;             float g[4], v[4];
;             g[0] = mp * pg.x * wg[0].x + cg_.x * wg[1].x + mn * ng.x * wg[2].x + bg.x;
;             g[1] = mp * pg.y * wg[0].y + cg_.y * wg[1].y + mn * ng.y * wg[2].y + bg.y;
;             g[2] = mp * pg.z * wg[0].z + cg_.z * wg[1].z + mn * ng.z * wg[2].z + bg.z;
;             g[3] = mp * pg.w * wg[0].w + cg_.w * wg[1].w + mn * ng.w * wg[2].w + bg.w;
;             v[0] = mp * pvv.x * wv[0].x + cv_.x * wv[1].x + mn * nv.x * wv[2].x + bv.x;
;             v[1] = mp * pvv.y * wv[0].y + cv_.y * wv[1].y + mn * nv.y * wv[2].y + bv.y;
;             v[2] = mp * pvv.z * wv[0].z + cv_.z * wv[1].z + mn * nv.z * wv[2].z + bv.z;
;             v[3] = mp * pvv.w * wv[0].w + cv_.w * wv[1].w + mn * nv.w * wv[2].w + bv.w;
;             float a_[4];
; #pragma unroll
;             for (int e = 0; e < 4; ++e) a_[e] = g[e] * __builtin_amdgcn_rcpf(1.f + fexp2(-1.4426950408889634f * g[e])) * v[e];
;             u32x2 ov = {pk_bf16(a_[0], a_[1]), pk_bf16(a_[2], a_[3])};
;             *(u32x2*)(Aout + (ptrdiff_t)R * DFF) = ov;
;           }
;           pg = cg_; pvv = cv_; cg_ = ng; cv_ = nv;
;         }
.Lcf0_s1:
	ds_read2_b64 v[34:37], v48 offset0:130 offset1:162
	s_waitcnt lgkmcnt(0)
	v_lshlrev_b32_e32 v56, 16, v34
	v_and_b32_e32 v57, 0xffff0000, v34
	v_add_u32_e32 v34, 1, v49
	v_lshlrev_b32_e32 v52, 16, v35
	v_and_b32_e32 v53, 0xffff0000, v35
	v_lshlrev_b32_e32 v54, 16, v36
	v_and_b32_e32 v55, 0xffff0000, v36
	v_lshlrev_b32_e32 v50, 16, v37
	v_and_b32_e32 v51, 0xffff0000, v37
	v_pk_mul_f32 v[40:41], v[10:11], v[66:67]
	v_pk_mul_f32 v[44:45], v[12:13], v[58:59]
	v_add_u32_e32 v74, 2, v0
	v_pk_fma_f32 v[40:41], v[2:3], v[68:69], v[40:41]
	v_pk_fma_f32 v[40:41], v[18:19], v[56:57], v[40:41]
	v_mov_b64_e32 v[68:69], v[72:73]
	v_pk_add_f32 v[40:41], v[26:27], v[40:41]
	v_pk_mul_f32 v[68:69], v[6:7], v[68:69]
	v_mul_f32_e32 v35, 0xbfb8aa3b, v40
	v_exp_f32_e32 v35, v35
	v_pk_fma_f32 v[68:69], v[14:15], v[70:71], v[68:69]
	v_pk_fma_f32 v[68:69], v[22:23], v[54:55], v[68:69]
	v_add_f32_e32 v35, 1.0, v35
	v_rcp_f32_e32 v72, v35
	v_mul_f32_e32 v35, 0xbfb8aa3b, v41
	v_exp_f32_e32 v35, v35
	v_pk_add_f32 v[68:69], v[30:31], v[68:69]
	v_add_f32_e32 v35, 1.0, v35
	v_rcp_f32_e32 v73, v35
	v_pk_fma_f32 v[44:45], v[4:5], v[60:61], v[44:45]
	v_mov_b64_e32 v[60:61], v[52:53]
	v_mov_b64_e32 v[34:35], v[64:65]
	v_pk_fma_f32 v[44:45], v[20:21], v[60:61], v[44:45]
	v_pk_mul_f32 v[34:35], v[8:9], v[34:35]
	v_pk_add_f32 v[44:45], v[28:29], v[44:45]
	v_pk_fma_f32 v[34:35], v[16:17], v[62:63], v[34:35]
	v_pk_fma_f32 v[34:35], v[24:25], v[50:51], v[34:35]
	v_mul_f32_e32 v36, 0xbfb8aa3b, v44
	v_mul_f32_e32 v37, 0xbfb8aa3b, v45
	v_exp_f32_e32 v36, v36
	v_exp_f32_e32 v37, v37
	v_pk_mul_f32 v[40:41], v[40:41], v[72:73]
	v_pk_add_f32 v[34:35], v[32:33], v[34:35]
	v_add_f32_e32 v36, 1.0, v36
	v_add_f32_e32 v37, 1.0, v37
	v_rcp_f32_e32 v36, v36
	v_rcp_f32_e32 v37, v37
	v_pk_mul_f32 v[40:41], v[68:69], v[40:41]
	v_pk_mul_f32 v[36:37], v[44:45], v[36:37]
	s_nop 0
	v_pk_mul_f32 v[34:35], v[34:35], v[36:37]
	v_cvt_pk_bf16_f32 v36, v40, v41
	v_cvt_pk_bf16_f32 v37, v34, v35
	v_mad_i64_i32 v[34:35], s[10:11], v74, s36, v[38:39]
	global_store_dwordx2 v[34:35], v[36:37], off
.Lcf0_s2:
	ds_read2_b64 v[34:37], v48 offset0:195 offset1:227
	v_add_u32_e32 v49, 2, v49
	s_waitcnt lgkmcnt(0)
	v_lshlrev_b32_e32 v40, 16, v34
	v_and_b32_e32 v41, 0xffff0000, v34
	v_lshlrev_b32_e32 v34, 16, v35
	v_and_b32_e32 v35, 0xffff0000, v35
	v_lshlrev_b32_e32 v44, 16, v36
	v_and_b32_e32 v45, 0xffff0000, v36
	v_lshlrev_b32_e32 v36, 16, v37
	v_and_b32_e32 v37, 0xffff0000, v37
	v_add_u32_e32 v65, 3, v0
	v_pk_mul_f32 v[68:69], v[10:11], v[56:57]
	v_pk_mul_f32 v[72:73], v[12:13], v[52:53]
	v_pk_fma_f32 v[66:67], v[2:3], v[66:67], v[68:69]
	v_pk_fma_f32 v[66:67], v[18:19], v[40:41], v[66:67]
	v_mov_b64_e32 v[68:69], v[70:71]
	v_pk_add_f32 v[66:67], v[26:27], v[66:67]
	v_pk_mul_f32 v[68:69], v[6:7], v[68:69]
	v_mul_f32_e32 v49, 0xbfb8aa3b, v66
	v_exp_f32_e32 v49, v49
	v_pk_fma_f32 v[68:69], v[14:15], v[54:55], v[68:69]
	v_pk_fma_f32 v[68:69], v[22:23], v[44:45], v[68:69]
	v_add_f32_e32 v49, 1.0, v49
	v_rcp_f32_e32 v70, v49
	v_mul_f32_e32 v49, 0xbfb8aa3b, v67
	v_exp_f32_e32 v49, v49
	v_pk_add_f32 v[68:69], v[30:31], v[68:69]
	v_pk_fma_f32 v[58:59], v[4:5], v[58:59], v[72:73]
	v_add_f32_e32 v49, 1.0, v49
	v_rcp_f32_e32 v71, v49
	v_mov_b64_e32 v[60:61], v[62:63]
	v_pk_mul_f32 v[60:61], v[8:9], v[60:61]
	v_pk_mul_f32 v[66:67], v[66:67], v[70:71]
	v_pk_fma_f32 v[60:61], v[16:17], v[50:51], v[60:61]
	v_pk_mul_f32 v[66:67], v[68:69], v[66:67]
	v_mov_b64_e32 v[68:69], v[34:35]
	v_pk_fma_f32 v[58:59], v[20:21], v[68:69], v[58:59]
	v_pk_fma_f32 v[60:61], v[24:25], v[36:37], v[60:61]
	v_pk_add_f32 v[58:59], v[28:29], v[58:59]
	v_pk_add_f32 v[60:61], v[32:33], v[60:61]
	v_mul_f32_e32 v49, 0xbfb8aa3b, v58
	v_exp_f32_e32 v49, v49
	s_nop 0
	v_add_f32_e32 v49, 1.0, v49
	v_rcp_f32_e32 v62, v49
	v_mul_f32_e32 v49, 0xbfb8aa3b, v59
	v_exp_f32_e32 v49, v49
	s_nop 0
	v_add_f32_e32 v49, 1.0, v49
	v_rcp_f32_e32 v63, v49
	s_nop 0
	v_pk_mul_f32 v[58:59], v[58:59], v[62:63]
	s_nop 0
	v_pk_mul_f32 v[58:59], v[60:61], v[58:59]
	v_cvt_pk_bf16_f32 v60, v66, v67
	v_cvt_pk_bf16_f32 v61, v58, v59
	v_mad_i64_i32 v[58:59], s[10:11], v65, s36, v[38:39]
	global_store_dwordx2 v[58:59], v[60:61], off
	s_branch .Lcf0_l

; template <int EPI>
; DI void phase_gemm(const Params& p, const GemmArgs& ga, char* lds) {
;     ...
;         const int R0 = 1 + seg * 16;
;         const int Rend = (R0 + 16 < 255) ? (R0 + 16) : 255;
;         auto ld4 = [&](const char* b_, int R) -> float4 {
;           const u32x2 u = *(const u32x2*)(b_ + R * RS);
;           float4 f = {__uint_as_float(u.x << 16), __uint_as_float(u.x & 0xffff0000u), __uint_as_float(u.y << 16), __uint_as_float(u.y & 0xffff0000u)};
;           return f;
;         };
;         float4 pg = ld4(gbase, R0 - 1), pvv = ld4(vbase, R0 - 1);
;         float4 cg_ = ld4(gbase, R0), cv_ = ld4(vbase, R0);
;         u16* Aout = (u16*)(p.ws + OFF_BIG) + (ptrdiff_t)(tokbase + pos0) * DFF + ch;
; #pragma unroll 4
;         for (int R = R0; R < Rend; ++R) {
;           const float4 ng = ld4(gbase, R + 1), nv = ld4(vbase, R + 1);
;           if (pos0 + R < S) {
;             const int tflat = pos0 + R;
;             const int ps = (tflat < NTOK_P) ? (tflat & (SP - 1)) : ((tflat - NTOK_P) & (SS - 1));
;             const int Ss = (tflat < NTOK_P) ? SP : SS;
.LBB0_179:
	s_or_b64 exec, exec, s[14:15]
	s_and_b64 s[10:11], exec, s[8:9]
	s_mov_b64 s[42:43], 0x3818900
	s_mov_b64 s[40:41], 0x3838900
	s_mov_b64 s[38:39], 0x3858900
	s_mov_b64 s[36:37], 0x27c0080
	s_mov_b64 exec, s[10:11]
	s_cbranch_execz .LBB0_165
	s_mul_i32 s10, s20, 0x1600
	s_mul_hi_i32 s11, s20, 0x1600
	s_add_u32 s10, s2, s10
	s_addc_u32 s11, s3, s11
	s_add_i32 s14, s27, -2
	v_lshl_add_u64 v[38:39], s[10:11], 0, v[46:47]
	s_mul_hi_i32 s10, s14, 0x1600
	s_mul_i32 s11, s14, 0x1600
	v_add_u32_e32 v50, 1, v0
	v_mov_b32_e32 v42, s11
	v_mov_b32_e32 v43, s10
	v_mad_i64_i32 v[50:51], s[10:11], v50, s46, 0
	v_mad_i64_i32 v[42:43], s[10:11], v0, s46, v[42:43]
	v_readlane_b32 s16, v254, 43
	v_mad_i64_i32 v[50:51], s[10:11], s14, v216, v[50:51]
	v_lshl_add_u64 v[42:43], v[42:43], 0, v[46:47]
	v_readlane_b32 s17, v254, 44
	v_lshl_add_u64 v[46:47], v[50:51], 0, v[46:47]
	v_mad_u64_u32 v[50:51], s[10:11], v0, s35, v[156:157]
	v_lshl_add_u64 v[42:43], s[16:17], 0, v[42:43]
	v_lshl_add_u64 v[46:47], s[16:17], 0, v[46:47]
	s_mov_b64 s[14:15], 0
	s_waitcnt vmcnt(0)
	s_ashr_i32 s10, s20, 11
	s_add_i32 s11, s20, 0xff
	s_ashr_i32 s11, s11, 11
	s_cmp_eq_u32 s10, s11
	s_cbranch_scc0 .LBB0_182
	s_cmp_lt_i32 s20, 0xbf02
	s_cbranch_scc1 .Lcf1_h
	s_branch .LBB0_182

; DI float fexp2(float x) { return __builtin_amdgcn_exp2f(x); }
; template <int EPI>
; DI void phase_gemm(const Params& p, const GemmArgs& ga, char* lds) {
;     ...
; #pragma unroll 4
;         for (int R = R0; R < Rend; ++R) {
;           const float4 ng = ld4(gbase, R + 1), nv = ld4(vbase, R + 1);
;           if (pos0 + R < S) {
;             const int tflat = pos0 + R;
;             const int ps = (tflat < NTOK_P) ? (tflat & (SP - 1)) : ((tflat - NTOK_P) & (SS - 1));
;             const int Ss = (tflat < NTOK_P) ? SP : SS;
;             const float mp = (ps == 0) ? 0.f : 1.f;
;             const float mn = (ps == Ss - 1) ? 0.f : 1.f;
;             float g[4], v[4];
;             g[0] = mp * pg.x * wg[0].x + cg_.x * wg[1].x + mn * ng.x * wg[2].x + bg.x;
;             g[1] = mp * pg.y * wg[0].y + cg_.y * wg[1].y + mn * ng.y * wg[2].y + bg.y;
;             g[2] = mp * pg.z * wg[0].z + cg_.z * wg[1].z + mn * ng.z * wg[2].z + bg.z;
;             g[3] = mp * pg.w * wg[0].w + cg_.w * wg[1].w + mn * ng.w * wg[2].w + bg.w;
;             v[0] = mp * pvv.x * wv[0].x + cv_.x * wv[1].x + mn * nv.x * wv[2].x + bv.x;
;             v[1] = mp * pvv.y * wv[0].y + cv_.y * wv[1].y + mn * nv.y * wv[2].y + bv.y;
;             v[2] = mp * pvv.z * wv[0].z + cv_.z * wv[1].z + mn * nv.z * wv[2].z + bv.z;
;             v[3] = mp * pvv.w * wv[0].w + cv_.w * wv[1].w + mn * nv.w * wv[2].w + bv.w;
;             float a_[4];
; #pragma unroll
;             for (int e = 0; e < 4; ++e) a_[e] = g[e] * __builtin_amdgcn_rcpf(1.f + fexp2(-1.4426950408889634f * g[e])) * v[e];
;             u32x2 ov = {pk_bf16(a_[0], a_[1]), pk_bf16(a_[2], a_[3])};
;             *(u32x2*)(Aout + (ptrdiff_t)R * DFF) = ov;
;           }
;           pg = cg_; pvv = cv_; cg_ = ng; cv_ = nv;
;         }
.Lcf1_l:
	v_add_u32_e32 v0, 4, v0
	v_cmp_ge_i32_e64 s[10:11], v0, v170
	v_lshl_add_u64 v[42:43], v[42:43], 0, s[86:87]
	v_lshl_add_u64 v[46:47], v[46:47], 0, s[86:87]
	s_or_b64 s[14:15], s[10:11], s[14:15]
	v_add_u32_e32 v50, 0x820, v50
	s_andn2_b64 exec, exec, s[14:15]
	s_cbranch_execz .LBB0_165
.Lcf1_h:
	ds_read2_b64 v[60:63], v50 offset1:32
	v_add_u32_e32 v51, s27, v0
	v_add_u32_e32 v58, -1, v51
	s_waitcnt lgkmcnt(0)
	v_lshlrev_b32_e32 v68, 16, v60
	v_and_b32_e32 v69, 0xffff0000, v60
	v_lshlrev_b32_e32 v60, 16, v61
	v_and_b32_e32 v61, 0xffff0000, v61
	v_lshlrev_b32_e32 v72, 16, v62
	v_and_b32_e32 v73, 0xffff0000, v62
	v_lshlrev_b32_e32 v64, 16, v63
	v_and_b32_e32 v65, 0xffff0000, v63
	v_pk_mul_f32 v[66:67], v[10:11], v[40:41]
	v_pk_mul_f32 v[70:71], v[12:13], v[34:35]
	v_pk_fma_f32 v[56:57], v[2:3], v[56:57], v[66:67]
	v_pk_fma_f32 v[56:57], v[18:19], v[68:69], v[56:57]
	v_pk_mul_f32 v[54:55], v[6:7], v[54:55]
	v_pk_add_f32 v[56:57], v[26:27], v[56:57]
	v_pk_fma_f32 v[54:55], v[14:15], v[44:45], v[54:55]
	v_mul_f32_e32 v59, 0xbfb8aa3b, v56
	v_exp_f32_e32 v59, v59
	v_pk_fma_f32 v[54:55], v[22:23], v[72:73], v[54:55]
	v_add_f32_e32 v59, 1.0, v59
	v_rcp_f32_e32 v66, v59
	v_mul_f32_e32 v59, 0xbfb8aa3b, v57
	v_exp_f32_e32 v59, v59
	v_pk_add_f32 v[54:55], v[30:31], v[54:55]
	v_add_f32_e32 v59, 1.0, v59
	v_rcp_f32_e32 v67, v59
	v_pk_fma_f32 v[52:53], v[4:5], v[52:53], v[70:71]
	v_pk_mul_f32 v[56:57], v[56:57], v[66:67]
	v_pk_mul_f32 v[48:49], v[8:9], v[48:49]
	v_pk_mul_f32 v[54:55], v[54:55], v[56:57]
	v_pk_fma_f32 v[52:53], v[20:21], v[60:61], v[52:53]
	v_pk_fma_f32 v[48:49], v[16:17], v[36:37], v[48:49]
	v_pk_add_f32 v[52:53], v[28:29], v[52:53]
	v_pk_fma_f32 v[48:49], v[24:25], v[64:65], v[48:49]
	v_mul_f32_e32 v56, 0xbfb8aa3b, v52
	v_mul_f32_e32 v57, 0xbfb8aa3b, v53
	v_exp_f32_e32 v56, v56
	v_exp_f32_e32 v57, v57
	v_pk_add_f32 v[48:49], v[32:33], v[48:49]
	v_add_f32_e32 v56, 1.0, v56
	v_add_f32_e32 v57, 1.0, v57
	v_rcp_f32_e32 v56, v56
	v_rcp_f32_e32 v57, v57
	s_nop 0
	v_pk_mul_f32 v[52:53], v[52:53], v[56:57]
	s_nop 0
	v_pk_mul_f32 v[48:49], v[48:49], v[52:53]
	v_cvt_pk_bf16_f32 v52, v54, v55
	v_cvt_pk_bf16_f32 v53, v48, v49
	global_store_dwordx2 v[42:43], v[52:53], off
.Lcf1_s0:
	ds_read2_b64 v[52:55], v50 offset0:65 offset1:97
	s_waitcnt lgkmcnt(0)
	v_lshlrev_b32_e32 v66, 16, v52
	v_and_b32_e32 v67, 0xffff0000, v52
	v_lshlrev_b32_e32 v58, 16, v53
	v_and_b32_e32 v59, 0xffff0000, v53
	v_lshlrev_b32_e32 v70, 16, v54
	v_and_b32_e32 v71, 0xffff0000, v54
	v_lshlrev_b32_e32 v62, 16, v55
	v_and_b32_e32 v63, 0xffff0000, v55
	v_pk_mul_f32 v[54:55], v[10:11], v[68:69]
	v_pk_mul_f32 v[56:57], v[12:13], v[60:61]
	v_pk_fma_f32 v[40:41], v[2:3], v[40:41], v[54:55]
	v_pk_fma_f32 v[40:41], v[18:19], v[66:67], v[40:41]
	v_pk_mul_f32 v[44:45], v[6:7], v[44:45]
	v_pk_add_f32 v[40:41], v[26:27], v[40:41]
	v_pk_fma_f32 v[44:45], v[14:15], v[72:73], v[44:45]
	v_mul_f32_e32 v49, 0xbfb8aa3b, v40
	v_exp_f32_e32 v49, v49
	v_pk_fma_f32 v[44:45], v[22:23], v[70:71], v[44:45]
	v_add_f32_e32 v49, 1.0, v49
	v_rcp_f32_e32 v54, v49
	v_mul_f32_e32 v49, 0xbfb8aa3b, v41
	v_exp_f32_e32 v49, v49
	v_pk_add_f32 v[44:45], v[30:31], v[44:45]
	v_add_f32_e32 v49, 1.0, v49
	v_rcp_f32_e32 v55, v49
	v_pk_fma_f32 v[34:35], v[4:5], v[34:35], v[56:57]
	v_pk_mul_f32 v[40:41], v[40:41], v[54:55]
	v_pk_mul_f32 v[36:37], v[8:9], v[36:37]
	v_pk_mul_f32 v[40:41], v[44:45], v[40:41]
	v_pk_fma_f32 v[34:35], v[20:21], v[58:59], v[34:35]
	v_pk_fma_f32 v[36:37], v[16:17], v[64:65], v[36:37]
	v_pk_add_f32 v[34:35], v[28:29], v[34:35]
	v_pk_fma_f32 v[36:37], v[24:25], v[62:63], v[36:37]
	v_mul_f32_e32 v44, 0xbfb8aa3b, v34
	v_mul_f32_e32 v45, 0xbfb8aa3b, v35
	v_exp_f32_e32 v44, v44
	v_exp_f32_e32 v45, v45
	v_pk_add_f32 v[36:37], v[32:33], v[36:37]
	v_add_f32_e32 v44, 1.0, v44
	v_add_f32_e32 v45, 1.0, v45
	v_rcp_f32_e32 v44, v44
	v_rcp_f32_e32 v45, v45
	s_nop 0
	v_pk_mul_f32 v[34:35], v[34:35], v[44:45]
	s_nop 0
	v_pk_mul_f32 v[34:35], v[36:37], v[34:35]
	v_cvt_pk_bf16_f32 v36, v40, v41
	v_cvt_pk_bf16_f32 v37, v34, v35
	global_store_dwordx2 v[46:47], v[36:37], off
; DI float fexp2(float x) { return __builtin_amdgcn_exp2f(x); }
; template <int EPI>
; DI void phase_gemm(const Params& p, const GemmArgs& ga, char* lds) {
;     ...
; #pragma unroll 4
;         for (int R = R0; R < Rend; ++R) {
;           const float4 ng = ld4(gbase, R + 1), nv = ld4(vbase, R + 1);
;           if (pos0 + R < S) {
;             const int tflat = pos0 + R;
;             const int ps = (tflat < NTOK_P) ? (tflat & (SP - 1)) : ((tflat - NTOK_P) & (SS - 1));
;             const int Ss = (tflat < NTOK_P) ? SP : SS;
;             const float mp = (ps == 0) ? 0.f : 1.f;
;             const float mn = (ps == Ss - 1) ? 0.f : 1.f;
;             float g[4], v[4];
;             g[0] = mp * pg.x * wg[0].x + cg_.x * wg[1].x + mn * ng.x * wg[2].x + bg.x;
;             g[1] = mp * pg.y * wg[0].y + cg_.y * wg[1].y + mn * ng.y * wg[2].y + bg.y;
;             g[2] = mp * pg.z * wg[0].z + cg_.z * wg[1].z + mn * ng.z * wg[2].z + bg.z;
;             g[3] = mp * pg.w * wg[0].w + cg_.w * wg[1].w + mn * ng.w * wg[2].w + bg.w;
;             v[0] = mp * pvv.x * wv[0].x + cv_.x * wv[1].x + mn * nv.x * wv[2].x + bv.x;
;             v[1] = mp * pvv.y * wv[0].y + cv_.y * wv[1].y + mn * nv.y * wv[2].y + bv.y;
;             v[2] = mp * pvv.z * wv[0].z + cv_.z * wv[1].z + mn * nv.z * wv[2].z + bv.z;
;             v[3] = mp * pvv.w * wv[0].w + cv_.w * wv[1].w + mn * nv.w * wv[2].w + bv.w;
;             float a_[4];
; #pragma unroll
;             for (int e = 0; e < 4; ++e) a_[e] = g[e] * __builtin_amdgcn_rcpf(1.f + fexp2(-1.4426950408889634f * g[e])) * v[e];
;             u32x2 ov = {pk_bf16(a_[0], a_[1]), pk_bf16(a_[2], a_[3])};
;             *(u32x2*)(Aout + (ptrdiff_t)R * DFF) = ov;
;           }
;           pg = cg_; pvv = cv_; cg_ = ng; cv_ = nv;
;         }
.Lcf1_s1:
	ds_read2_b64 v[34:37], v50 offset0:130 offset1:162
	s_waitcnt lgkmcnt(0)
	v_lshlrev_b32_e32 v56, 16, v34
	v_and_b32_e32 v57, 0xffff0000, v34
	v_add_u32_e32 v34, 1, v51
	v_lshlrev_b32_e32 v52, 16, v35
	v_and_b32_e32 v53, 0xffff0000, v35
	v_lshlrev_b32_e32 v54, 16, v36
	v_and_b32_e32 v55, 0xffff0000, v36
	v_lshlrev_b32_e32 v48, 16, v37
	v_and_b32_e32 v49, 0xffff0000, v37
	v_pk_mul_f32 v[40:41], v[10:11], v[66:67]
	v_pk_mul_f32 v[44:45], v[12:13], v[58:59]
	v_add_u32_e32 v74, 2, v0
	v_pk_fma_f32 v[40:41], v[2:3], v[68:69], v[40:41]
	v_pk_fma_f32 v[40:41], v[18:19], v[56:57], v[40:41]
	v_mov_b64_e32 v[68:69], v[72:73]
	v_pk_add_f32 v[40:41], v[26:27], v[40:41]
	v_pk_mul_f32 v[68:69], v[6:7], v[68:69]
	v_mul_f32_e32 v35, 0xbfb8aa3b, v40
	v_exp_f32_e32 v35, v35
	v_pk_fma_f32 v[68:69], v[14:15], v[70:71], v[68:69]
	v_pk_fma_f32 v[68:69], v[22:23], v[54:55], v[68:69]
	v_add_f32_e32 v35, 1.0, v35
	v_rcp_f32_e32 v72, v35
	v_mul_f32_e32 v35, 0xbfb8aa3b, v41
	v_exp_f32_e32 v35, v35
	v_pk_add_f32 v[68:69], v[30:31], v[68:69]
	v_add_f32_e32 v35, 1.0, v35
	v_rcp_f32_e32 v73, v35
	v_pk_fma_f32 v[44:45], v[4:5], v[60:61], v[44:45]
	v_mov_b64_e32 v[60:61], v[52:53]
	v_mov_b64_e32 v[34:35], v[64:65]
	v_pk_fma_f32 v[44:45], v[20:21], v[60:61], v[44:45]
	v_pk_mul_f32 v[34:35], v[8:9], v[34:35]
	v_pk_add_f32 v[44:45], v[28:29], v[44:45]
	v_pk_fma_f32 v[34:35], v[16:17], v[62:63], v[34:35]
	v_pk_fma_f32 v[34:35], v[24:25], v[48:49], v[34:35]
	v_mul_f32_e32 v36, 0xbfb8aa3b, v44
	v_mul_f32_e32 v37, 0xbfb8aa3b, v45
	v_exp_f32_e32 v36, v36
	v_exp_f32_e32 v37, v37
	v_pk_mul_f32 v[40:41], v[40:41], v[72:73]
	v_pk_add_f32 v[34:35], v[32:33], v[34:35]
	v_add_f32_e32 v36, 1.0, v36
	v_add_f32_e32 v37, 1.0, v37
	v_rcp_f32_e32 v36, v36
	v_rcp_f32_e32 v37, v37
	v_pk_mul_f32 v[40:41], v[68:69], v[40:41]
	v_pk_mul_f32 v[36:37], v[44:45], v[36:37]
	s_nop 0
	v_pk_mul_f32 v[34:35], v[34:35], v[36:37]
	v_cvt_pk_bf16_f32 v36, v40, v41
	v_cvt_pk_bf16_f32 v37, v34, v35
	v_mad_i64_i32 v[34:35], s[10:11], v74, s46, v[38:39]
	global_store_dwordx2 v[34:35], v[36:37], off
.Lcf1_s2:
	ds_read2_b64 v[34:37], v50 offset0:195 offset1:227
	v_add_u32_e32 v51, 2, v51
	s_waitcnt lgkmcnt(0)
	v_lshlrev_b32_e32 v40, 16, v34
	v_and_b32_e32 v41, 0xffff0000, v34
	v_lshlrev_b32_e32 v34, 16, v35
	v_and_b32_e32 v35, 0xffff0000, v35
	v_lshlrev_b32_e32 v44, 16, v36
	v_and_b32_e32 v45, 0xffff0000, v36
	v_lshlrev_b32_e32 v36, 16, v37
	v_and_b32_e32 v37, 0xffff0000, v37
	v_add_u32_e32 v65, 3, v0
	v_pk_mul_f32 v[68:69], v[10:11], v[56:57]
	v_pk_mul_f32 v[72:73], v[12:13], v[52:53]
	v_pk_fma_f32 v[66:67], v[2:3], v[66:67], v[68:69]
	v_pk_fma_f32 v[66:67], v[18:19], v[40:41], v[66:67]
	v_mov_b64_e32 v[68:69], v[70:71]
	v_pk_add_f32 v[66:67], v[26:27], v[66:67]
	v_pk_mul_f32 v[68:69], v[6:7], v[68:69]
	v_mul_f32_e32 v51, 0xbfb8aa3b, v66
	v_exp_f32_e32 v51, v51
	v_pk_fma_f32 v[68:69], v[14:15], v[54:55], v[68:69]
	v_pk_fma_f32 v[68:69], v[22:23], v[44:45], v[68:69]
	v_add_f32_e32 v51, 1.0, v51
	v_rcp_f32_e32 v70, v51
	v_mul_f32_e32 v51, 0xbfb8aa3b, v67
	v_exp_f32_e32 v51, v51
	v_pk_add_f32 v[68:69], v[30:31], v[68:69]
	v_pk_fma_f32 v[58:59], v[4:5], v[58:59], v[72:73]
	v_add_f32_e32 v51, 1.0, v51
	v_rcp_f32_e32 v71, v51
	v_mov_b64_e32 v[60:61], v[62:63]
	v_pk_mul_f32 v[60:61], v[8:9], v[60:61]
	v_pk_mul_f32 v[66:67], v[66:67], v[70:71]
	v_pk_fma_f32 v[60:61], v[16:17], v[48:49], v[60:61]
	v_pk_mul_f32 v[66:67], v[68:69], v[66:67]
	v_mov_b64_e32 v[68:69], v[34:35]
	v_pk_fma_f32 v[58:59], v[20:21], v[68:69], v[58:59]
	v_pk_fma_f32 v[60:61], v[24:25], v[36:37], v[60:61]
	v_pk_add_f32 v[58:59], v[28:29], v[58:59]
	v_pk_add_f32 v[60:61], v[32:33], v[60:61]
	v_mul_f32_e32 v51, 0xbfb8aa3b, v58
	v_exp_f32_e32 v51, v51
	s_nop 0
	v_add_f32_e32 v51, 1.0, v51
	v_rcp_f32_e32 v62, v51
	v_mul_f32_e32 v51, 0xbfb8aa3b, v59
	v_exp_f32_e32 v51, v51
	s_nop 0
	v_add_f32_e32 v51, 1.0, v51
	v_rcp_f32_e32 v63, v51
	s_nop 0
	v_pk_mul_f32 v[58:59], v[58:59], v[62:63]
	s_nop 0
	v_pk_mul_f32 v[58:59], v[60:61], v[58:59]
	v_cvt_pk_bf16_f32 v60, v66, v67
	v_cvt_pk_bf16_f32 v61, v58, v59
	v_mad_i64_i32 v[58:59], s[10:11], v65, s46, v[38:39]
	global_store_dwordx2 v[58:59], v[60:61], off
	s_branch .Lcf1_l
